# GQA heads: softmax reference = Cauchy-Schwarz score bound from the q/k gains (exact softmax, runtime fallback); main loop skips the row-max section
# speedup vs baseline: 1.0149x; 1.0081x over previous
; __global__ void __launch_bounds__(NTHREADS, 2) fwd_megakernel(Args a) {
;     __shared__ __attribute__((aligned(16))) unsigned char lds[LDS_TOTAL];
;     cg::grid_group grid = cg::this_grid();
;     const int tid = threadIdx.x, lane = tid & 63, wave = __builtin_amdgcn_readfirstlane(tid >> 6);
;     const int G = gridDim.x, bx = blockIdx.x;
;     const int vcu = (G % 8 == 0) ? (bx % 8) * (G / 8) + bx / 8 : bx;
;     const int gw = vcu * NWAVES + wave, NGW = G * NWAVES;
_Z14fwd_megakernel4Args:
	s_load_dwordx2 s[34:35], s[0:1], 0xc0
	s_mov_b32 s98, 0
	s_mov_b32 s99, 0xff800000
	s_add_u32 s10, s0, 0xc0
	s_addc_u32 s11, s1, 0
	v_and_b32_e32 v222, 0x3ff, v0
	v_writelane_b32 v254, s2, 0
	s_waitcnt lgkmcnt(0)
	s_and_b32 s4, s34, 7
	v_readfirstlane_b32 s3, v222
	s_cmp_lg_u32 s4, 0
	s_cbranch_scc1 .LBB0_2
	s_ashr_i32 s5, s2, 31
	s_lshr_b32 s5, s5, 29
	s_add_i32 s5, s2, s5
	s_and_b32 s6, s5, -8
	s_ashr_i32 s4, s34, 3
	s_sub_i32 s6, s2, s6
	s_mul_i32 s4, s4, s6
	s_ashr_i32 s5, s5, 3
	s_add_i32 s4, s4, s5
	v_writelane_b32 v254, s4, 0

; #define FRESH_LANE() ({ int t_ = threadIdx.x; asm volatile("" : "+v"(t_)); t_ & 63; })
; template <int l> __device__ __forceinline__ void layer_body(const Args& a, unsigned char* lds, const XcdBarrier& bar, int G, int bx, int vcu, int gw, int NGW, int lane_, int tid_k, int wave) {
;     ...
;             const int lane = FRESH_LANE();
;             for (int row = gw; row < MROWS; row += NGW) {
;                 const int b = row / TPB, t = row - b * TPB; const bool islat = t >= CTXL; const int pos = t - CTXL;
;                 unsigned* rp = (unsigned*)(QKV + (size_t)row * PAR_IN + 1536);
; #pragma unroll
;                 for (int j = 0; j < 5; ++j) { const int p = lane + 64 * j, head = p >> 5, i = p & 31; const unsigned w = rp[p];
;                     float x1 = bflo(w), x2 = bfhi(w); float ss = x1 * x1 + x2 * x2;
; #pragma unroll
;                     for (int o = 1; o < 32; o <<= 1) ss += __shfl_xor(ss, o);
;                     const float rstd = 1.0f / sqrtf(ss * (1.0f / 64.0f) + EPS); const float* gn = head < 8 ? a.q_gain : a.k_gain;
;                     x1 = x1 * rstd * gn[2 * i]; x2 = x2 * rstd * gn[2 * i + 1];
;                     if (islat) { const int pp = (i < 16) ? (pos >> 6) : (pos & 63); const float cs = ROPE[(pp * 16 + (i & 15)) * 2], sn = ROPE[(pp * 16 + (i & 15)) * 2 + 1];
.LBB0_248:
	s_or_b64 exec, exec, s[4:5]
	s_waitcnt lgkmcnt(0)
	v_cndmask_b32_e64 v0, 0, 1, s[6:7]
	s_add_u32 s50, s30, 0x2fbc000
	v_cmp_ne_u32_e64 s[0:1], 1, v0
	s_addc_u32 s51, s31, 0
	v_mov_b32_e32 v4, v222
	v_writelane_b32 v254, s0, 6
	s_andn2_b64 vcc, exec, s[6:7]
	v_mbcnt_lo_u32_b32 v223, -1, 0
	s_barrier
	v_writelane_b32 v254, s1, 7
	s_cbranch_vccnz .LBB0_261
	v_and_b32_e32 v5, 31, v4
	v_lshlrev_b32_e32 v6, 3, v5
	global_load_dwordx2 v[0:1], v6, s[60:61]
	global_load_dwordx2 v[2:3], v6, s[62:63]
	v_mbcnt_hi_u32_b32 v7, -1, v223
	v_and_b32_e32 v6, 63, v4
	v_and_b32_e32 v8, 64, v7
	v_lshlrev_b32_e32 v4, 1, v4
	v_add_u32_e32 v8, 64, v8
	v_and_b32_e32 v16, 30, v4
	v_xor_b32_e32 v4, 1, v7
	v_cmp_lt_i32_e32 vcc, v4, v8
	v_cmp_gt_u32_e64 s[4:5], 16, v5
	v_mov_b32_e32 v5, 0
	v_cndmask_b32_e32 v4, v7, v4, vcc
	v_lshlrev_b32_e32 v17, 2, v4
	v_xor_b32_e32 v4, 2, v7
	v_cmp_lt_i32_e32 vcc, v4, v8
	v_mov_b32_e32 v22, 0x1200
	s_mov_b64 s[10:11], 0xc00
	v_cndmask_b32_e32 v4, v7, v4, vcc
	v_lshlrev_b32_e32 v18, 2, v4
	v_xor_b32_e32 v4, 4, v7
	v_cmp_lt_i32_e32 vcc, v4, v8
	s_mov_b32 s0, 0xffff0000
	v_mov_b32_e32 v23, 0x358637bd
	v_cndmask_b32_e32 v4, v7, v4, vcc
	v_lshlrev_b32_e32 v19, 2, v4
	v_xor_b32_e32 v4, 8, v7
	v_cmp_lt_i32_e32 vcc, v4, v8
	s_mov_b32 s1, 0xf800000
	v_mov_b32_e32 v24, 0x260
	v_cndmask_b32_e32 v4, v7, v4, vcc
	v_lshlrev_b32_e32 v20, 2, v4
	v_xor_b32_e32 v4, 16, v7
	v_cmp_lt_i32_e32 vcc, v4, v8
	s_mov_b32 s48, 0x3e38aa3b
	s_movk_i32 s3, 0x7fff
	v_cndmask_b32_e32 v4, v7, v4, vcc
	v_lshlrev_b32_e32 v21, 2, v4
	v_lshlrev_b32_e32 v4, 2, v6
	v_lshl_add_u64 v[6:7], s[44:45], 0, v[4:5]
	v_mov_b32_e32 v25, 1
	s_mov_b32 s12, s38
	s_waitcnt vmcnt(0)
	v_max_f32_e64 v8, |v0|, |v1|
	v_max_f32_e64 v9, |v2|, |v3|
	ds_bpermute_b32 v10, v17, v8
	ds_bpermute_b32 v11, v17, v9
	s_waitcnt lgkmcnt(0)
	v_max_f32_e32 v8, v8, v10
	v_max_f32_e32 v9, v9, v11
	ds_bpermute_b32 v10, v18, v8
	ds_bpermute_b32 v11, v18, v9
	s_waitcnt lgkmcnt(0)
	v_max_f32_e32 v8, v8, v10
	v_max_f32_e32 v9, v9, v11
	ds_bpermute_b32 v10, v19, v8
	ds_bpermute_b32 v11, v19, v9
	s_waitcnt lgkmcnt(0)
	v_max_f32_e32 v8, v8, v10
	v_max_f32_e32 v9, v9, v11
	ds_bpermute_b32 v10, v20, v8
	ds_bpermute_b32 v11, v20, v9
	s_waitcnt lgkmcnt(0)
	v_max_f32_e32 v8, v8, v10
	v_max_f32_e32 v9, v9, v11
	ds_bpermute_b32 v10, v21, v8
	ds_bpermute_b32 v11, v21, v9
	s_waitcnt lgkmcnt(0)
	v_max_f32_e32 v8, v8, v10
	v_max_f32_e32 v9, v9, v11
	v_mul_f32_e32 v8, v8, v9
	v_mul_f32_e32 v8, 0x413c5bc0, v8
	s_nop 0
	v_readfirstlane_b32 s99, v8
	s_cmp_le_u32 s99, 0x42200000
	s_cselect_b32 s98, 1, 0
	s_cselect_b32 s99, s99, 0xff800000
	s_min_i32 vcc_lo, s12, 0x83ff
	s_mul_hi_i32 s6, vcc_lo, 0x3e0f83e1
	s_lshr_b32 s7, s6, 31
	s_ashr_i32 s6, s6, 11
	s_add_i32 s6, s6, s7
	s_mulk_i32 s6, 0x2100
	s_sub_i32 s6, vcc_lo, s6
	s_mul_i32 s7, vcc_lo, 0x1200
	s_add_u32 s8, s44, s7
	s_addc_u32 s9, s45, 0
	s_add_u32 s8, s8, 0xc00
	s_addc_u32 s9, s9, 0
	s_add_i32 s7, s6, 0xffffff00
	s_lshr_b32 s7, s7, 6
	s_cmpk_gt_i32 s6, 0xff
	s_cselect_b32 s52, 1, 0
	s_cselect_b32 s7, s7, 0
	s_and_b32 s6, s6, 63
	s_cmp_lg_u32 s52, 0
	s_cselect_b32 s6, s6, 0
	v_mov_b32_e32 v8, s6
	v_mov_b32_e32 v9, s7
	v_cndmask_b32_e64 v8, v8, v9, s[4:5]
	v_lshl_or_b32 v8, v8, 5, v16
	v_lshlrev_b32_e32 v8, 2, v8
	global_load_dword v26, v4, s[8:9]
	global_load_dword v27, v4, s[8:9] offset:256
	global_load_dword v28, v4, s[8:9] offset:512
	global_load_dword v29, v4, s[8:9] offset:768
	global_load_dword v30, v4, s[8:9] offset:1024
	global_load_dwordx2 v[32:33], v8, s[50:51]
	global_load_dword v82, v4, s[8:9]
	global_load_dword v83, v4, s[8:9]
	global_load_dword v84, v4, s[8:9]
	global_load_dword v85, v4, s[8:9]
	global_load_dword v86, v4, s[8:9]

; #define WAIT_BAR(N) asm volatile("s_waitcnt vmcnt(" #N ") lgkmcnt(0)\n\ts_barrier":::"memory")
;   #define DMA_K(t,slot) glds16(ksrc+(long)KROW(t)*PK,(unsigned)__builtin_amdgcn_readfirstlane(kdst+(slot)))
;   #define DMA_V(t,slot) do{ glds16(vsrc+(long)KROW(t)*PV,(unsigned)__builtin_amdgcn_readfirstlane(vdst+2*(slot))); if(MODE==2)glds16(vsrc+(long)KROW(t)*PV+64,(unsigned)__builtin_amdgcn_readfirstlane(vdst+2*(slot)+SLOTB)); }while(0)
;   #define CMASK(P0,P1,t) do{ if(MODE==1&&(t)>=4)na_apply(P0,P1,mf,na_rowok((t),nabase,nar)); }while(0)
;   #define START(P0,P1) do{ const float rm=rowmax(P0,P1); resc=false; \
;     { const float dl=rm; mhat=fadd_s(mhat,dl); \
;       _Pragma("unroll") for(int r=0;r<16;++r){P0[r]=fsub_s(P0[r],dl);P1[r]=fsub_s(P1[r],dl);} \
;       _Pragma("unroll") for(int r=0;r<16;++r)negm[r]=-mhat; asm volatile("":"+v"(negm)); } \
;     _Pragma("unroll") for(int r=0;r<16;++r)P0[r]=__builtin_amdgcn_exp2f(P0[r]); }while(0)
;   #define ROT() do{sl_prev=sl_cur;sl_cur=sl_next;sl_next=(sl_next==(NSLOT-1)*SLOTB)?0:sl_next+SLOTB;}while(0)
; template<int MODE,int THRL> __device__ __forceinline__ void attn_unit(const bf16*Qw0,int PQ,const bf16*__restrict__ Kh,int PK,const bf16*__restrict__ Vh,int PV,bf16*Ow0,int PO,int NT,int nabase,int nar0,const float*rpbh,char*shm,int&rot,bool pre,bool hasn,long dKn,long dVn){
;     ...
;   if(pre){WAIT_BAR(0);}else if(MODE==2){WAIT_BAR(4);}else{WAIT_BAR(3);}
;   qkt(pA0,pA1,Kbase+sl_cur,qr,negm,r32,hi);asm volatile("s_nop 15\n\ts_nop 7":"+v"(pA0),"+v"(pA1));CMASK(pA0,pA1,0);
;   START(pA0,pA1);
;   _Pragma("unroll") for(int r=0;r<16;++r)pA1[r]=__builtin_amdgcn_exp2f(pA1[r]);
;   WAIT_BAR(0);
;   DMA_K(3,sl_cur);DMA_V(1,sl_next);
;   ROT();
;   kload8(kf,kp0+sl_cur);
;   if(MODE==2){WAIT_BAR(3);}else{WAIT_BAR(2);}
.LBB0_486:
	v_lshlrev_b32_e32 v0, 10, v214
	v_lshlrev_b32_e32 v35, 4, v213
	v_add3_u32 v44, s82, v0, v35
	ds_read_b128 v[36:39], v44
	ds_read_b128 v[40:43], v44 offset:512
	v_or_b32_e32 v221, v0, v35
	s_add_i32 s10, s15, s82
	s_waitcnt vmcnt(3) lgkmcnt(1)
	v_mfma_f32_32x32x16_bf16 v[18:33], v[36:39], v[148:151], v[2:17]
	v_lshl_add_u64 v[196:197], v[206:207], 0, s[54:55]
	s_and_b32 s3, s3, 0x3fffffc0
	s_lshl_b32 s3, s3, 2
	s_add_i32 s3, s3, 0x12000
	s_mov_b32 s86, 1
	v_lshlrev_b32_e32 v224, 4, v214
	v_lshl_add_u32 v218, v213, 2, s3
	s_waitcnt lgkmcnt(0)
	v_mfma_f32_32x32x16_bf16 v[2:17], v[40:43], v[148:151], v[2:17]
	ds_read_b128 v[36:39], v44 offset:2048
	ds_read_b128 v[40:43], v44 offset:2560
	s_waitcnt vmcnt(2) lgkmcnt(1)
	v_mfma_f32_32x32x16_bf16 v[18:33], v[36:39], v[140:143], v[18:33]
	s_waitcnt lgkmcnt(0)
	v_mfma_f32_32x32x16_bf16 v[2:17], v[40:43], v[140:143], v[2:17]
	ds_read_b128 v[36:39], v44 offset:4096
	ds_read_b128 v[40:43], v44 offset:4608
	s_waitcnt vmcnt(1) lgkmcnt(1)
	v_mfma_f32_32x32x16_bf16 v[18:33], v[36:39], v[132:135], v[18:33]
	s_waitcnt lgkmcnt(0)
	v_mfma_f32_32x32x16_bf16 v[2:17], v[40:43], v[132:135], v[2:17]
	ds_read_b128 v[36:39], v44 offset:6144
	ds_read_b128 v[40:43], v44 offset:6656
	s_waitcnt vmcnt(0) lgkmcnt(1)
	v_mfma_f32_32x32x16_bf16 v[18:33], v[36:39], v[128:131], v[18:33]
	v_lshlrev_b32_e32 v36, 1, v34
	v_lshlrev_b32_e32 v34, 4, v34
	v_and_b32_e32 v34, 0xc0, v34
	v_lshl_or_b32 v217, v214, 8, v34
	v_and_b32_e32 v216, 32, v36
	v_or3_b32 v220, v216, v215, v217
	s_waitcnt lgkmcnt(0)
	v_mfma_f32_32x32x16_bf16 v[2:17], v[40:43], v[128:131], v[2:17]
	s_nop 15
	s_nop 7
	s_nop 0
	v_max3_f32 v0, v18, v19, v2
	v_max3_f32 v34, v20, v21, v3
	s_nop 0
	v_max3_f32 v0, v0, v4, v5
	v_max3_f32 v34, v34, v24, v25
	s_nop 0
	v_max3_f32 v0, v0, v22, v23
	v_max3_f32 v34, v34, v8, v9
	s_nop 0
	v_max3_f32 v0, v0, v6, v7
	v_max3_f32 v34, v34, v28, v29
	s_nop 0
	v_max3_f32 v0, v0, v26, v27
	v_max3_f32 v34, v34, v12, v13
	s_nop 0
	v_max3_f32 v0, v0, v10, v11
	v_max3_f32 v34, v34, v32, v33
	s_nop 0
	v_max3_f32 v0, v0, v30, v31
	v_max3_f32 v34, v34, v16, v17
	s_nop 0
	v_max3_f32 v0, v0, v14, v15
	s_nop 0
	v_max_f32_e32 v0, v0, v34
	s_nop 0
	v_mov_b32_e32 v34, v0
	s_nop 1
	v_permlane32_swap_b32_e32 v0, v34
	v_max_f32_e32 v0, v0, v34
	s_nop 0
	v_max_f32_e32 v0, s99, v0
	v_add_f32_e32 v219, v1, v0
	v_sub_f32_e32 v2, v2, v0
	v_sub_f32_e32 v3, v3, v0
	v_sub_f32_e32 v18, v18, v0
	v_sub_f32_e32 v19, v19, v0
	v_sub_f32_e32 v20, v20, v0
	s_nop 0
	v_xor_b32_e32 v48, 0x80000000, v219
	v_mov_b32_e32 v49, v48
	v_mov_b32_e32 v50, v48
	v_mov_b32_e32 v51, v48
	v_mov_b32_e32 v52, v48
	v_mov_b32_e32 v53, v48
	v_mov_b32_e32 v54, v48
	v_mov_b32_e32 v55, v48
	v_mov_b32_e32 v56, v48
	v_mov_b32_e32 v57, v48
	v_mov_b32_e32 v58, v48
	v_mov_b32_e32 v59, v48
	v_mov_b32_e32 v60, v48
	v_mov_b32_e32 v61, v48
	v_mov_b32_e32 v62, v48
	v_mov_b32_e32 v63, v48
	s_waitcnt vmcnt(0) lgkmcnt(0)
	s_barrier
	v_sub_f32_e32 v4, v4, v0
	v_sub_f32_e32 v21, v21, v0
	v_sub_f32_e32 v5, v5, v0
	v_sub_f32_e32 v22, v22, v0
	v_sub_f32_e32 v6, v6, v0
	v_sub_f32_e32 v23, v23, v0
	v_sub_f32_e32 v7, v7, v0
	v_sub_f32_e32 v24, v24, v0
	v_sub_f32_e32 v8, v8, v0
	v_sub_f32_e32 v25, v25, v0
	v_sub_f32_e32 v9, v9, v0
	v_sub_f32_e32 v26, v26, v0
	v_sub_f32_e32 v10, v10, v0
	v_sub_f32_e32 v27, v27, v0
	v_sub_f32_e32 v11, v11, v0
	v_sub_f32_e32 v28, v28, v0
	v_sub_f32_e32 v12, v12, v0
	v_sub_f32_e32 v29, v29, v0
	v_sub_f32_e32 v13, v13, v0
	v_sub_f32_e32 v30, v30, v0
	v_sub_f32_e32 v14, v14, v0
	v_sub_f32_e32 v31, v31, v0
	v_sub_f32_e32 v15, v15, v0
	v_sub_f32_e32 v32, v32, v0
	v_sub_f32_e32 v16, v16, v0
	v_sub_f32_e32 v33, v33, v0
	v_sub_f32_e32 v0, v17, v0
	v_exp_f32_e32 v64, v2
	v_exp_f32_e32 v65, v3
	v_lshl_add_u64 v[2:3], v[204:205], 0, s[58:59]
	s_mov_b32 s11, m0
	s_mov_b32 m0, s10
	s_nop 0
	global_load_lds_dwordx4 v[2:3], off
	s_mov_b32 m0, s11
	s_lshl_b32 s10, s43, 1
	v_exp_f32_e32 v79, v0
	s_add_i32 s10, s10, s33
	s_mov_b32 s11, m0
	s_mov_b32 m0, s10
	s_nop 0
	global_load_lds_dwordx4 v[196:197], off
	s_mov_b32 m0, s11
	v_add_u32_e32 v0, s43, v221
	ds_read_b128 v[188:191], v0
	ds_read_b128 v[184:187], v0 offset:512
	ds_read_b128 v[180:183], v0 offset:2048
	ds_read_b128 v[176:179], v0 offset:2560
	ds_read_b128 v[172:175], v0 offset:4096
	ds_read_b128 v[168:171], v0 offset:4608
	ds_read_b128 v[164:167], v0 offset:6144
	ds_read_b128 v[160:163], v0 offset:6656
	v_exp_f32_e32 v80, v18
	v_exp_f32_e32 v81, v19
	v_exp_f32_e32 v82, v20
	v_exp_f32_e32 v83, v21
	v_exp_f32_e32 v84, v22
	v_exp_f32_e32 v85, v23
	v_exp_f32_e32 v86, v24
	v_exp_f32_e32 v87, v25
	v_exp_f32_e32 v88, v26
	v_exp_f32_e32 v89, v27
	v_exp_f32_e32 v90, v28
	v_exp_f32_e32 v91, v29
	v_exp_f32_e32 v92, v30
	v_exp_f32_e32 v93, v31
	v_exp_f32_e32 v94, v32
	v_exp_f32_e32 v95, v33
	v_exp_f32_e32 v66, v4
	v_exp_f32_e32 v67, v5
	v_exp_f32_e32 v68, v6
	v_exp_f32_e32 v69, v7
	v_exp_f32_e32 v70, v8
	v_exp_f32_e32 v71, v9
	v_exp_f32_e32 v72, v10
	v_exp_f32_e32 v73, v11
	v_exp_f32_e32 v74, v12
	v_exp_f32_e32 v75, v13
	v_exp_f32_e32 v76, v14
	v_exp_f32_e32 v77, v15
	v_exp_f32_e32 v78, v16
	s_waitcnt vmcnt(2) lgkmcnt(0)
	s_barrier
	s_cmpk_lg_i32 s43, 0x4000
	s_cselect_b32 s52, s52, 0
	s_andn2_b64 vcc, exec, s[8:9]
	v_cmp_gt_u32_e64 s[8:9], 32, v211
	s_cbranch_vccnz .LBB0_502
	v_mov_b32_e32 v14, v1
	v_mov_b32_e32 v15, v1
	s_mov_b64 s[10:11], 0x168000
	v_mov_b32_e32 v0, v1
	v_mov_b32_e32 v2, v1
	v_mov_b32_e32 v3, v1
	v_mov_b32_e32 v4, v1
	v_mov_b32_e32 v5, v1
	v_mov_b32_e32 v6, v1
	v_mov_b32_e32 v7, v1
	v_mov_b32_e32 v8, v1
	v_mov_b32_e32 v9, v1
	v_mov_b32_e32 v10, v1
	v_mov_b32_e32 v11, v1
	v_mov_b32_e32 v12, v1
	v_mov_b32_e32 v13, v1
	v_mov_b64_e32 v[46:47], v[14:15]
	v_mov_b64_e32 v[30:31], v[14:15]
	v_lshl_add_u64 v[198:199], v[206:207], 0, s[58:59]
	v_lshl_add_u64 v[200:201], v[204:205], 0, s[10:11]
	v_mov_b32_e32 v225, 0
	s_mov_b32 s67, 6
	v_mov_b64_e32 v[44:45], v[12:13]
	v_mov_b64_e32 v[42:43], v[10:11]
	v_mov_b64_e32 v[40:41], v[8:9]
	v_mov_b64_e32 v[38:39], v[6:7]
	v_mov_b64_e32 v[36:37], v[4:5]
	v_mov_b64_e32 v[34:35], v[2:3]
	v_mov_b64_e32 v[32:33], v[0:1]
	v_mov_b64_e32 v[28:29], v[12:13]
	v_mov_b64_e32 v[26:27], v[10:11]
	v_mov_b64_e32 v[24:25], v[8:9]
	v_mov_b64_e32 v[22:23], v[6:7]
	v_mov_b64_e32 v[20:21], v[4:5]
	v_mov_b64_e32 v[18:19], v[2:3]
	v_mov_b64_e32 v[16:17], v[0:1]
.LBB0_488:
	v_lshl_add_u32 v0, s82, 1, v220
	ds_read_b64_tr_b16 v[192:193], v0 offset:24576
	ds_read_b64_tr_b16 v[194:195], v0 offset:25088
	s_waitcnt lgkmcnt(9)
	v_mfma_f32_32x32x16_bf16 v[112:127], v[188:191], v[148:151], v[48:63]
	v_add_f32_e32 v2, v80, v81
	v_add_f32_e32 v2, v82, v2
	v_add_f32_e32 v2, v83, v2
	v_add_f32_e32 v2, v84, v2
	v_add_f32_e32 v2, v85, v2
	v_cvt_pk_bf16_f32 v156, v80, v81
	v_cvt_pk_bf16_f32 v157, v82, v83
	ds_read_b64_tr_b16 v[188:189], v0 offset:28672
	ds_read_b64_tr_b16 v[190:191], v0 offset:29184
	s_waitcnt lgkmcnt(10)
	v_mfma_f32_32x32x16_bf16 v[96:111], v[184:187], v[148:151], v[48:63]
	v_add_f32_e32 v2, v86, v2
	v_add_f32_e32 v2, v87, v2
	v_add_f32_e32 v2, v88, v2
	v_add_f32_e32 v2, v89, v2
	v_cvt_pk_bf16_f32 v158, v84, v85
	v_cvt_pk_bf16_f32 v159, v86, v87
	ds_read_b64_tr_b16 v[184:185], v0 offset:25600
	ds_read_b64_tr_b16 v[186:187], v0 offset:26112
	s_waitcnt lgkmcnt(11)
	v_mfma_f32_32x32x16_bf16 v[112:127], v[180:183], v[140:143], v[112:127]
	v_add_f32_e32 v2, v90, v2
	v_add_f32_e32 v2, v91, v2
	v_add_f32_e32 v2, v92, v2
	v_add_f32_e32 v2, v93, v2
	v_cvt_pk_bf16_f32 v152, v88, v89
	v_cvt_pk_bf16_f32 v153, v90, v91
	ds_read_b64_tr_b16 v[84:85], v0 offset:29696
	ds_read_b64_tr_b16 v[86:87], v0 offset:30208
	s_waitcnt lgkmcnt(12)
	v_mfma_f32_32x32x16_bf16 v[96:111], v[176:179], v[140:143], v[96:111]
	v_add_f32_e32 v2, v94, v2
	v_add_f32_e32 v2, v95, v2
	v_add_f32_e32 v2, v64, v2
	v_add_f32_e32 v2, v65, v2
	v_cvt_pk_bf16_f32 v154, v92, v93
	v_cvt_pk_bf16_f32 v155, v94, v95
	ds_read_b64_tr_b16 v[80:81], v0 offset:26624
	ds_read_b64_tr_b16 v[82:83], v0 offset:27136
	s_waitcnt lgkmcnt(13)
	v_mfma_f32_32x32x16_bf16 v[112:127], v[172:175], v[132:135], v[112:127]
	v_add_f32_e32 v2, v66, v2
	v_add_f32_e32 v2, v67, v2
	v_add_f32_e32 v2, v68, v2
	v_add_f32_e32 v2, v69, v2
	v_cvt_pk_bf16_f32 v144, v64, v65
	v_cvt_pk_bf16_f32 v145, v66, v67
	ds_read_b64_tr_b16 v[10:11], v0 offset:30720
	ds_read_b64_tr_b16 v[12:13], v0 offset:31232
	s_waitcnt lgkmcnt(14)
	v_mfma_f32_32x32x16_bf16 v[96:111], v[168:171], v[132:135], v[96:111]
	v_add_f32_e32 v2, v70, v2
	v_add_f32_e32 v2, v71, v2
	v_add_f32_e32 v2, v72, v2
	v_add_f32_e32 v2, v73, v2
	v_cvt_pk_bf16_f32 v146, v68, v69
	v_cvt_pk_bf16_f32 v147, v70, v71
	ds_read_b64_tr_b16 v[6:7], v0 offset:27648
	ds_read_b64_tr_b16 v[8:9], v0 offset:28160
	s_waitcnt lgkmcnt(14)
	v_mfma_f32_32x32x16_bf16 v[112:127], v[164:167], v[128:131], v[112:127]
	v_add_f32_e32 v2, v74, v2
	v_add_f32_e32 v2, v75, v2
	v_add_f32_e32 v2, v76, v2
	v_add_f32_e32 v14, v77, v2
	v_cvt_pk_bf16_f32 v136, v72, v73
	v_cvt_pk_bf16_f32 v137, v74, v75
	ds_read_b64_tr_b16 v[2:3], v0 offset:31744
	ds_read_b64_tr_b16 v[4:5], v0 offset:32256
	v_mfma_f32_32x32x16_bf16 v[96:111], v[160:163], v[128:131], v[96:111]
	v_add_f32_e32 v0, v78, v14
	v_add_f32_e32 v0, v79, v0
	v_cvt_pk_bf16_f32 v138, v76, v77
	v_cvt_pk_bf16_f32 v139, v78, v79
	v_lshl_add_u64 v[14:15], v[200:201], 0, s[60:61]
	s_add_i32 s10, s43, s15
	s_mov_b32 s11, m0
	s_mov_b32 m0, s10
	s_nop 0
	global_load_lds_dwordx4 v[14:15], off
	s_mov_b32 m0, s11
	v_lshl_add_u64 v[14:15], v[198:199], 0, s[60:61]
	s_lshl_b32 s10, s52, 1
	s_add_i32 s10, s10, s33
	s_mov_b32 s11, m0
	s_mov_b32 m0, s10
	s_nop 0
	global_load_lds_dwordx4 v[14:15], off
	s_mov_b32 m0, s11
	s_cmp_lg_u32 s98, 0
	s_cbranch_scc1 .Lbm_skip_a
	v_max_f32_e32 v14, v112, v113
	v_max3_f32 v15, v114, v115, v97
	v_max3_f32 v14, v14, v96, v98
	v_max3_f32 v14, v14, v99, v116
	v_max3_f32 v15, v15, v118, v119
	v_max3_f32 v14, v14, v117, v100
	v_max3_f32 v15, v15, v102, v103
	v_max3_f32 v14, v14, v101, v120
	v_max3_f32 v15, v15, v122, v123
	v_max3_f32 v14, v14, v121, v104
	v_max3_f32 v15, v15, v106, v107
	v_max3_f32 v14, v14, v105, v124
	v_max3_f32 v15, v15, v126, v127
	v_max3_f32 v64, v14, v125, v108
	v_max3_f32 v15, v15, v110, v111
	v_add_f32_e32 v14, v225, v0
	v_max3_f32 v0, v64, v109, v15
	v_mov_b32_e32 v15, v0
	s_nop 1
	v_permlane32_swap_b32_e32 v0, v15
	v_max_f32_e32 v0, v0, v15
	v_cmp_lt_f32_e32 vcc, s13, v0
	s_cmp_lg_u64 vcc, 0
	s_cselect_b64 s[10:11], -1, 0
	s_cbranch_vccnz .LBB0_496
	s_branch .LBB0_489
.Lbm_skip_a:
	v_add_f32_e32 v14, v225, v0
	s_mov_b64 s[10:11], 0

.LBB0_491:
	s_add_i32 s10, s52, 0x2000
	s_cmpk_lg_i32 s52, 0x4000
	s_cselect_b32 s80, s10, 0
	v_lshl_add_u32 v4, s43, 1, v220
	ds_read_b64_tr_b16 v[168:169], v4 offset:24576
	ds_read_b64_tr_b16 v[170:171], v4 offset:25088
	s_waitcnt lgkmcnt(9)
	v_mfma_f32_32x32x16_bf16 v[80:95], v[64:67], v[148:151], v[48:63]
	v_add_f32_e32 v2, v112, v113
	v_add_f32_e32 v2, v114, v2
	v_add_f32_e32 v2, v115, v2
	v_add_f32_e32 v2, v116, v2
	v_add_f32_e32 v2, v117, v2
	v_cvt_pk_bf16_f32 v156, v112, v113
	v_cvt_pk_bf16_f32 v157, v114, v115
	ds_read_b64_tr_b16 v[164:165], v4 offset:28672
	ds_read_b64_tr_b16 v[166:167], v4 offset:29184
	s_waitcnt lgkmcnt(10)
	v_mfma_f32_32x32x16_bf16 v[64:79], v[160:163], v[148:151], v[48:63]
	v_add_f32_e32 v2, v118, v2
	v_add_f32_e32 v2, v119, v2
	v_add_f32_e32 v2, v120, v2
	v_add_f32_e32 v2, v121, v2
	v_cvt_pk_bf16_f32 v158, v116, v117
	v_cvt_pk_bf16_f32 v159, v118, v119
	ds_read_b64_tr_b16 v[160:161], v4 offset:25600
	ds_read_b64_tr_b16 v[162:163], v4 offset:26112
	s_waitcnt lgkmcnt(11)
	v_mfma_f32_32x32x16_bf16 v[80:95], v[192:195], v[140:143], v[80:95]
	v_add_f32_e32 v2, v122, v2
	v_add_f32_e32 v2, v123, v2
	v_add_f32_e32 v2, v124, v2
	v_add_f32_e32 v2, v125, v2
	v_cvt_pk_bf16_f32 v152, v120, v121
	v_cvt_pk_bf16_f32 v153, v122, v123
	ds_read_b64_tr_b16 v[116:117], v4 offset:29696
	ds_read_b64_tr_b16 v[118:119], v4 offset:30208
	s_waitcnt lgkmcnt(12)
	v_mfma_f32_32x32x16_bf16 v[64:79], v[184:187], v[140:143], v[64:79]
	v_add_f32_e32 v2, v126, v2
	v_add_f32_e32 v2, v127, v2
	v_add_f32_e32 v2, v96, v2
	v_add_f32_e32 v2, v97, v2
	v_cvt_pk_bf16_f32 v154, v124, v125
	v_cvt_pk_bf16_f32 v155, v126, v127
	ds_read_b64_tr_b16 v[112:113], v4 offset:26624
	ds_read_b64_tr_b16 v[114:115], v4 offset:27136
	s_waitcnt lgkmcnt(13)
	v_mfma_f32_32x32x16_bf16 v[80:95], v[188:191], v[132:135], v[80:95]
	v_add_f32_e32 v2, v98, v2
	v_add_f32_e32 v2, v99, v2
	v_add_f32_e32 v2, v100, v2
	v_add_f32_e32 v2, v101, v2
	v_cvt_pk_bf16_f32 v144, v96, v97
	v_cvt_pk_bf16_f32 v145, v98, v99
	ds_read_b64_tr_b16 v[10:11], v4 offset:30720
	ds_read_b64_tr_b16 v[12:13], v4 offset:31232
	s_waitcnt lgkmcnt(14)
	v_mfma_f32_32x32x16_bf16 v[64:79], v[176:179], v[132:135], v[64:79]
	v_add_f32_e32 v2, v102, v2
	v_add_f32_e32 v2, v103, v2
	v_add_f32_e32 v2, v104, v2
	v_add_f32_e32 v2, v105, v2
	v_cvt_pk_bf16_f32 v146, v100, v101
	v_cvt_pk_bf16_f32 v147, v102, v103
	ds_read_b64_tr_b16 v[6:7], v4 offset:27648
	ds_read_b64_tr_b16 v[8:9], v4 offset:28160
	s_waitcnt lgkmcnt(14)
	v_mfma_f32_32x32x16_bf16 v[80:95], v[180:183], v[128:131], v[80:95]
	v_add_f32_e32 v2, v106, v2
	v_add_f32_e32 v2, v107, v2
	v_add_f32_e32 v2, v108, v2
	v_add_f32_e32 v15, v109, v2
	v_cvt_pk_bf16_f32 v136, v104, v105
	v_cvt_pk_bf16_f32 v137, v106, v107
	ds_read_b64_tr_b16 v[2:3], v4 offset:31744
	ds_read_b64_tr_b16 v[4:5], v4 offset:32256
	v_mfma_f32_32x32x16_bf16 v[64:79], v[172:175], v[128:131], v[64:79]
	v_add_f32_e32 v15, v110, v15
	v_add_f32_e32 v15, v111, v15
	v_cvt_pk_bf16_f32 v138, v108, v109
	v_cvt_pk_bf16_f32 v139, v110, v111
	s_cmp_lg_u32 s98, 0
	s_cbranch_scc1 .Lbm_skip_b
	v_max_f32_e32 v96, v81, v81
	v_max_f32_e32 v97, v80, v80
	v_max_f32_e32 v96, v97, v96
	s_nop 3
	s_nop 0
	v_max3_f32 v97, v82, v83, v65
	v_max3_f32 v96, v96, v64, v66
	v_max3_f32 v96, v96, v67, v84
	v_max3_f32 v97, v97, v86, v87
	v_max3_f32 v96, v96, v85, v68
	v_max3_f32 v97, v97, v70, v71
	v_max3_f32 v96, v96, v69, v88
	v_max3_f32 v97, v97, v90, v91
	v_max3_f32 v96, v96, v89, v72
	v_max3_f32 v97, v97, v74, v75
	v_max3_f32 v96, v96, v73, v92
	v_max3_f32 v97, v97, v94, v95
	v_max3_f32 v96, v96, v93, v76
	v_max3_f32 v97, v97, v78, v79
	v_add_f32_e32 v225, v14, v15
	v_max3_f32 v14, v96, v77, v97
	v_mov_b32_e32 v15, v14
	s_nop 1
	v_permlane32_swap_b32_e32 v14, v15
	s_add_i32 s10, s52, s15
	s_mov_b32 s11, m0
	s_mov_b32 m0, s10
	s_nop 0
	global_load_lds_dwordx4 v[200:201], off
	s_mov_b32 m0, s11
	s_lshl_b32 s10, s80, 1
	v_max_f32_e32 v14, v14, v15
	s_add_i32 s10, s10, s33
	s_mov_b32 s11, m0
	s_mov_b32 m0, s10
	s_nop 0
	global_load_lds_dwordx4 v[198:199], off
	s_mov_b32 m0, s11
	v_cmp_lt_f32_e32 vcc, s13, v14
	s_cmp_lg_u64 vcc, 0
	s_cselect_b64 s[10:11], -1, 0
	s_cbranch_vccnz .LBB0_499
	s_branch .LBB0_492
.Lbm_skip_b:
	v_add_f32_e32 v225, v14, v15
	s_add_i32 s10, s52, s15
	s_mov_b32 s11, m0
	s_mov_b32 m0, s10
	s_nop 0
	global_load_lds_dwordx4 v[200:201], off
	s_mov_b32 m0, s11
	s_lshl_b32 s10, s80, 1
	s_add_i32 s10, s10, s33
	s_mov_b32 s11, m0
	s_mov_b32 m0, s10
	s_nop 0
	global_load_lds_dwordx4 v[198:199], off
	s_mov_b32 m0, s11
	s_mov_b64 s[10:11], 0

; __global__ void __launch_bounds__(NTHREADS, 2) fwd_megakernel(Args a) {
;     __shared__ __attribute__((aligned(16))) unsigned char lds[LDS_TOTAL];
	.amdhsa_kernel _Z14fwd_megakernel4Args
		.amdhsa_group_segment_fixed_size 147456
		.amdhsa_private_segment_fixed_size 0
		.amdhsa_kernarg_size 448
		.amdhsa_user_sgpr_count 2
		.amdhsa_user_sgpr_dispatch_ptr 0
		.amdhsa_user_sgpr_queue_ptr 0
		.amdhsa_user_sgpr_kernarg_segment_ptr 1
		.amdhsa_user_sgpr_dispatch_id 0
		.amdhsa_user_sgpr_kernarg_preload_length 0
		.amdhsa_user_sgpr_kernarg_preload_offset 0
		.amdhsa_user_sgpr_private_segment_size 0
		.amdhsa_uses_dynamic_stack 0
		.amdhsa_enable_private_segment 0
		.amdhsa_system_sgpr_workgroup_id_x 1
		.amdhsa_system_sgpr_workgroup_id_y 0
		.amdhsa_system_sgpr_workgroup_id_z 0
		.amdhsa_system_sgpr_workgroup_info 0
		.amdhsa_system_vgpr_workitem_id 2
		.amdhsa_next_free_vgpr 255
		.amdhsa_next_free_sgpr 100
		.amdhsa_accum_offset 256
		.amdhsa_reserve_vcc 1
		.amdhsa_float_round_mode_32 0
		.amdhsa_float_round_mode_16_64 0
		.amdhsa_float_denorm_mode_32 3
		.amdhsa_float_denorm_mode_16_64 3
		.amdhsa_dx10_clamp 1
		.amdhsa_ieee_mode 1
		.amdhsa_fp16_overflow 0
		.amdhsa_tg_split 0
		.amdhsa_exception_fp_ieee_invalid_op 0
		.amdhsa_exception_fp_denorm_src 0
		.amdhsa_exception_fp_ieee_div_zero 0
		.amdhsa_exception_fp_ieee_overflow 0
		.amdhsa_exception_fp_ieee_underflow 0
		.amdhsa_exception_fp_ieee_inexact 0
		.amdhsa_exception_int_div_zero 0
	.end_amdhsa_kernel

; __global__ void __launch_bounds__(NTHREADS, 2) fwd_megakernel(Args a) {
;     __shared__ __attribute__((aligned(16))) unsigned char lds[LDS_TOTAL];
amdhsa.kernels:
  - .agpr_count:     0
    .args:
      - .offset:         0
        .size:           192
        .value_kind:     by_value
      - .offset:         192
        .size:           4
        .value_kind:     hidden_block_count_x
      - .offset:         196
        .size:           4
        .value_kind:     hidden_block_count_y
      - .offset:         200
        .size:           4
        .value_kind:     hidden_block_count_z
      - .offset:         204
        .size:           2
        .value_kind:     hidden_group_size_x
      - .offset:         206
        .size:           2
        .value_kind:     hidden_group_size_y
      - .offset:         208
        .size:           2
        .value_kind:     hidden_group_size_z
      - .offset:         210
        .size:           2
        .value_kind:     hidden_remainder_x
      - .offset:         212
        .size:           2
        .value_kind:     hidden_remainder_y
      - .offset:         214
        .size:           2
        .value_kind:     hidden_remainder_z
      - .offset:         232
        .size:           8
        .value_kind:     hidden_global_offset_x
      - .offset:         240
        .size:           8
        .value_kind:     hidden_global_offset_y
      - .offset:         248
        .size:           8
        .value_kind:     hidden_global_offset_z
      - .offset:         256
        .size:           2
        .value_kind:     hidden_grid_dims
      - .offset:         280
        .size:           8
        .value_kind:     hidden_multigrid_sync_arg
    .group_segment_fixed_size: 147456
    .kernarg_segment_align: 8
    .kernarg_segment_size: 448
    .language:       OpenCL C
    .language_version:
      - 2
      - 0
    .max_flat_workgroup_size: 512
    .name:           _Z14fwd_megakernel4Args
    .private_segment_fixed_size: 0
    .sgpr_count:     106
    .sgpr_spill_count: 32
    .symbol:         _Z14fwd_megakernel4Args.kd
    .uniform_work_group_size: 1
    .uses_dynamic_stack: false
    .vgpr_count:     255
    .vgpr_spill_count: 0
    .wavefront_size: 64
